# HGRN2 recurrence hot loop: q/P/k/D LDS fragment reads hoisted to the top of each chunk (one LDS round trip instead of four), counted lgkmcnt
# baseline (speedup 1.0000x reference)
; #define LAS __attribute__((address_space(3)))
; __device__ __forceinline__ unsigned pk2(float lo, float hi) { return pg8::cvt_pk_bf16(lo, hi); }
; __device__ __forceinline__ void hg_recur(LAS unsigned char* lds, const bf16_t* QF, bf16_t* IG, const bf16_t* P, const float* Dg, float* ssq_o, int G, int bid) {
;     ...
;             if (c > 0) H3_FLUSH(c - 1, st ^ 1);
;             f32x4 o0 = (f32x4){0.f, 0.f, 0.f, 0.f}, o1 = o0;
; #pragma unroll
;             for (int k2 = 0; k2 < 2; ++k2) {
;                 u32x2 sbu; sbu.x = pk2(S[k2][0], S[k2][1]); sbu.y = pk2(S[k2][2], S[k2][3]);
;                 const s16x4 Sb = __builtin_bit_cast(s16x4, sbu);
;                 const LAS unsigned char* qp = sb + H3_Q + lv * H3_QP + (32 * kq + 16 * k2 + 4 * fq) * 2;
;                 const s16x4 a0 = *(const LAS s16x4*)qp, a1 = *(const LAS s16x4*)(qp + 16 * H3_QP);
;                 o0 = __builtin_amdgcn_mfma_f32_16x16x16bf16_1k(a0, Sb, o0, 0, 0, 0);
;                 o1 = __builtin_amdgcn_mfma_f32_16x16x16bf16_1k(a1, Sb, o1, 0, 0, 0);
;             }
;             if (kq < 3) {
;                 const LAS unsigned char* pp = sb + H3_P + (16 * (kq > 0 ? 1 : 0) + lv) * H3_PP + (16 * (kq == 2 ? 1 : 0) + 4 * fq) * 2;
;                 const s16x4 a = *(const LAS s16x4*)pp;
;                 if (kq == 0) o0 = __builtin_amdgcn_mfma_f32_16x16x16bf16_1k(a, vf0, o0, 0, 0, 0);
;                 else if (kq == 1) o1 = __builtin_amdgcn_mfma_f32_16x16x16bf16_1k(a, vf0, o1, 0, 0, 0);
;                 else o1 = __builtin_amdgcn_mfma_f32_16x16x16bf16_1k(a, vf1, o1, 0, 0, 0);
.LBB0_504:
	ds_read2st64_b64 v[78:81], v90 offset0:32 offset1:40
	ds_read2st64_b64 v[112:115], v90 offset0:48 offset1:56
	ds_read_u16 v33, v98 offset:21504
	ds_read_u16 v39, v98 offset:21584
	ds_read_u16 v32, v98 offset:21664
	ds_read_u16 v34, v98 offset:21744
	ds_read_u16 v36, v98 offset:22784
	ds_read_u16 v35, v98 offset:22864
	ds_read_u16 v37, v98 offset:22944
	ds_read_u16 v38, v98 offset:23024
	s_waitcnt lgkmcnt(10)
	ds_read_b64 v[130:131], v99
	ds_read_b64 v[132:133], v99 offset:4352
	ds_read_b64 v[134:135], v99 offset:32
	ds_read_b64 v[136:137], v99 offset:4384
	s_waitcnt lgkmcnt(4)
	ds_read_b64 v[138:139], v100 offset:18944
	ds_read2_b64 v[140:143], v61 offset0:64 offset1:68
	ds_read_b128 v[144:147], v101 offset:24064
	ds_read_b128 v[148:151], v103 offset:24064
	ds_read2_b64 v[152:155], v107 offset0:64 offset1:68
	s_nop 0
	v_mov_b32_e32 v82, v78
	s_nop 0
	v_mov_b32_e32 v83, v112
	v_mov_b32_e32 v116, v80
	v_mov_b32_e32 v117, v114
	v_pk_add_f32 v[82:83], v[82:83], v[116:117]
	v_mov_b32_e32 v112, v79
	v_mov_b32_e32 v114, v81
	v_add_f32_e32 v73, v82, v83
	v_pk_add_f32 v[78:79], v[112:113], v[114:115]
	s_nop 0
	v_add_f32_e32 v80, v78, v79
	v_cvt_pk_bf16_f32 v81, v73, v80
	v_mul_f32_e32 v73, v73, v73
	v_fmac_f32_e32 v73, v80, v80
	v_add_co_u32_e32 v78, vcc, s3, v76
	s_nop 0
	v_add_f32_dpp v73, v73, v73 row_ror:8 row_mask:0xf bank_mask:0xf bound_ctrl:1
	v_addc_co_u32_e32 v79, vcc, -1, v77, vcc
	s_nop 0
	v_add_f32_dpp v73, v73, v73 row_ror:4 row_mask:0xf bank_mask:0xf bound_ctrl:1
	global_store_dword v[78:79], v81, off
	s_nop 0
	v_add_f32_dpp v73, v73, v73 row_ror:2 row_mask:0xf bank_mask:0xf bound_ctrl:1
	s_nop 1
	v_mov_b32_dpp v78, v73 row_ror:1 row_mask:0xf bank_mask:0xf bound_ctrl:1
	s_and_saveexec_b64 s[58:59], s[14:15]
	s_cbranch_execz .LBB0_506
	v_add_f32_e32 v73, v73, v78
	global_atomic_add_f32 v[74:75], v73, off offset:-1024
.LBB0_506:
	s_or_b64 exec, exec, s[58:59]
	v_cvt_pk_bf16_f32 v112, v28, v29
	v_cvt_pk_bf16_f32 v113, v30, v31
	s_nop 0
	s_nop 0
	v_cvt_pk_bf16_f32 v116, v24, v25
	v_cvt_pk_bf16_f32 v117, v26, v27
	s_nop 0
	s_nop 0
	s_waitcnt lgkmcnt(8)
	v_mfma_f32_16x16x16_bf16 v[80:83], v[130:131], v[112:113], 0
	v_lshlrev_b32_e32 v39, 16, v39
	v_or_b32_sdwa v78, v39, v33 dst_sel:DWORD dst_unused:UNUSED_PAD src0_sel:DWORD src1_sel:WORD_0
	v_lshlrev_b32_e32 v33, 16, v34
	s_waitcnt lgkmcnt(7)
	v_mfma_f32_16x16x16_bf16 v[112:115], v[132:133], v[112:113], 0
	v_lshlrev_b32_e32 v39, 16, v35
	v_or_b32_sdwa v79, v33, v32 dst_sel:DWORD dst_unused:UNUSED_PAD src0_sel:DWORD src1_sel:WORD_0
	s_waitcnt lgkmcnt(6)
	v_mfma_f32_16x16x16_bf16 v[32:35], v[134:135], v[116:117], v[80:83]
	s_nop 2
	v_or_b32_sdwa v80, v39, v36 dst_sel:DWORD dst_unused:UNUSED_PAD src0_sel:DWORD src1_sel:WORD_0
	v_lshlrev_b32_e32 v36, 16, v38
	v_or_b32_sdwa v81, v36, v37 dst_sel:DWORD dst_unused:UNUSED_PAD src0_sel:DWORD src1_sel:WORD_0
	s_waitcnt lgkmcnt(5)
	v_mfma_f32_16x16x16_bf16 v[36:39], v[136:137], v[116:117], v[112:115]
	s_and_saveexec_b64 s[58:59], s[16:17]
	s_cbranch_execz .LBB0_516
	s_nop 0
	s_and_saveexec_b64 s[36:37], s[42:43]
	s_xor_b64 s[60:61], exec, s[36:37]
	s_cbranch_execz .LBB0_513
	s_and_saveexec_b64 s[36:37], s[18:19]
	s_xor_b64 s[62:63], exec, s[36:37]
	s_cbranch_execz .LBB0_510
	s_waitcnt lgkmcnt(4)
	v_mfma_f32_16x16x16_bf16 v[36:39], v[138:139], v[80:81], v[36:39]
.LBB0_510:
	s_andn2_saveexec_b64 s[62:63], s[62:63]
	s_cbranch_execz .LBB0_512
	s_waitcnt lgkmcnt(4)
	v_mfma_f32_16x16x16_bf16 v[36:39], v[138:139], v[78:79], v[36:39]

; #define LAS __attribute__((address_space(3)))
; __device__ __forceinline__ void hg_recur(LAS unsigned char* lds, const bf16_t* QF, bf16_t* IG, const bf16_t* P, const float* Dg, float* ssq_o, int G, int bid) {
;     ...
;             if (kq < 3) {
;                 const LAS unsigned char* pp = sb + H3_P + (16 * (kq > 0 ? 1 : 0) + lv) * H3_PP + (16 * (kq == 2 ? 1 : 0) + 4 * fq) * 2;
;                 const s16x4 a = *(const LAS s16x4*)pp;
;                 if (kq == 0) o0 = __builtin_amdgcn_mfma_f32_16x16x16bf16_1k(a, vf0, o0, 0, 0, 0);
;                 else if (kq == 1) o1 = __builtin_amdgcn_mfma_f32_16x16x16bf16_1k(a, vf0, o1, 0, 0, 0);
;                 else o1 = __builtin_amdgcn_mfma_f32_16x16x16bf16_1k(a, vf1, o1, 0, 0, 0);
;             }
.LBB0_513:
	s_andn2_saveexec_b64 s[60:61], s[60:61]
	s_cbranch_execz .LBB0_515
	s_waitcnt lgkmcnt(4)
	v_mfma_f32_16x16x16_bf16 v[32:35], v[138:139], v[78:79], v[32:35]

; #define LAS __attribute__((address_space(3)))
; #define LDS_BARRIER() do { asm volatile("s_waitcnt lgkmcnt(0)" ::: "memory"); __builtin_amdgcn_s_barrier(); asm volatile("" ::: "memory"); } while (0)
; __device__ __forceinline__ void hg_recur(LAS unsigned char* lds, const bf16_t* QF, bf16_t* IG, const bf16_t* P, const float* Dg, float* ssq_o, int G, int bid) {
;     ...
; #pragma unroll
;             for (int k2 = 0; k2 < 2; ++k2) {
;                 const f32x4 dd = *(const LAS f32x4*)(sb + H3_D + (32 * kq + 16 * k2 + 4 * fq) * 4);
;                 S[k2] = S[k2] * dd;
;                 const LAS unsigned char* kp = sb + H3_K + (32 * kq + 16 * k2 + lv) * H3_KP + 4 * fq * 2;
;                 const s16x4 a0 = *(const LAS s16x4*)kp, a1 = *(const LAS s16x4*)(kp + 32);
;                 S[k2] = __builtin_amdgcn_mfma_f32_16x16x16bf16_1k(a0, vf0, S[k2], 0, 0, 0);
;                 S[k2] = __builtin_amdgcn_mfma_f32_16x16x16bf16_1k(a1, vf1, S[k2], 0, 0, 0);
;             }
;             { LAS float* ot = (LAS float*)(lds + H3_O + st * H3_OBYTES) + kq * 1024 + 16 * vt + lv;
; #pragma unroll
;               for (int i = 0; i < 4; ++i) { ot[(4 * fq + i) * 32] = o0[i]; ot[(16 + 4 * fq + i) * 32] = o1[i]; } }
;             LDS_BARRIER();
.LBB0_516:
	s_or_b64 exec, exec, s[58:59]
	s_nop 0
	s_nop 0
	s_nop 0
	s_add_i32 s36, s35, 1
	s_cmpk_gt_u32 s36, 0xfe
	s_waitcnt lgkmcnt(2)
	v_pk_mul_f32 v[30:31], v[30:31], v[146:147]
	v_pk_mul_f32 v[28:29], v[28:29], v[144:145]
	s_nop 0
	s_waitcnt lgkmcnt(1)
	v_pk_mul_f32 v[26:27], v[26:27], v[150:151]
	v_pk_mul_f32 v[24:25], v[24:25], v[148:149]
	v_mfma_f32_16x16x16_bf16 v[28:31], v[140:141], v[78:79], v[28:31]
	ds_write2_b32 v92, v32, v33 offset1:32
	ds_write2_b32 v108, v36, v37 offset1:32
	ds_write2_b32 v92, v34, v35 offset0:64 offset1:96
	ds_write2_b32 v108, v38, v39 offset0:64 offset1:96
	s_waitcnt lgkmcnt(0)
	s_waitcnt lgkmcnt(4)
	v_mfma_f32_16x16x16_bf16 v[24:27], v[152:153], v[78:79], v[24:27]
	s_barrier
	v_mfma_f32_16x16x16_bf16 v[28:31], v[142:143], v[80:81], v[28:31]
	v_mfma_f32_16x16x16_bf16 v[24:27], v[154:155], v[80:81], v[24:27]
	s_cbranch_scc1 .LBB0_528
	s_waitcnt vmcnt(2)
	ds_write_b128 v105, v[8:11]
	s_waitcnt vmcnt(1)
	ds_write_b128 v97, v[12:15] offset:8704
	s_and_saveexec_b64 s[36:37], s[8:9]
	s_xor_b64 s[58:59], exec, s[36:37]
	s_cbranch_execz .LBB0_525
	s_and_saveexec_b64 s[36:37], s[10:11]
	s_xor_b64 s[60:61], exec, s[36:37]
	s_cbranch_execz .LBB0_522
	s_and_saveexec_b64 s[62:63], s[12:13]
	v_add_u32_e32 v32, 0, v86
	ds_write_b128 v32, v[0:3] offset:19968
	s_or_b64 exec, exec, s[62:63]

; #define LAS __attribute__((address_space(3)))
; __device__ __forceinline__ unsigned pk2(float lo, float hi) { return pg8::cvt_pk_bf16(lo, hi); }
; __device__ __forceinline__ void hg_recur(LAS unsigned char* lds, const bf16_t* QF, bf16_t* IG, const bf16_t* P, const float* Dg, float* ssq_o, int G, int bid) {
;     ...
;             u32x2 vfu[2];
; #pragma unroll
;             for (int ss = 0; ss < 2; ++ss) {
;                 const LAS unsigned char* vp = sb + H3_V + (16 * ss + 4 * fq) * H3_VP + (16 * vt + lv) * 2;
;                 const unsigned e0 = *(const LAS bf16_t*)(vp), e1 = *(const LAS bf16_t*)(vp + H3_VP), e2 = *(const LAS bf16_t*)(vp + 2 * H3_VP), e3 = *(const LAS bf16_t*)(vp + 3 * H3_VP);
;                 vfu[ss].x = e0 | (e1 << 16); vfu[ss].y = e2 | (e3 << 16);
;             }
;             const s16x4 vf0 = __builtin_bit_cast(s16x4, vfu[0]), vf1 = __builtin_bit_cast(s16x4, vfu[1]);
;             if (c > 0) H3_FLUSH(c - 1, st ^ 1);
;             f32x4 o0 = (f32x4){0.f, 0.f, 0.f, 0.f}, o1 = o0;
; #pragma unroll
;             for (int k2 = 0; k2 < 2; ++k2) {
;                 u32x2 sbu; sbu.x = pk2(S[k2][0], S[k2][1]); sbu.y = pk2(S[k2][2], S[k2][3]);
;                 const s16x4 Sb = __builtin_bit_cast(s16x4, sbu);
;                 const LAS unsigned char* qp = sb + H3_Q + lv * H3_QP + (32 * kq + 16 * k2 + 4 * fq) * 2;
;                 const s16x4 a0 = *(const LAS s16x4*)qp, a1 = *(const LAS s16x4*)(qp + 16 * H3_QP);
;                 o0 = __builtin_amdgcn_mfma_f32_16x16x16bf16_1k(a0, Sb, o0, 0, 0, 0);
;                 o1 = __builtin_amdgcn_mfma_f32_16x16x16bf16_1k(a1, Sb, o1, 0, 0, 0);
;             }
;             if (kq < 3) {
;                 const LAS unsigned char* pp = sb + H3_P + (16 * (kq > 0 ? 1 : 0) + lv) * H3_PP + (16 * (kq == 2 ? 1 : 0) + 4 * fq) * 2;
;                 const s16x4 a = *(const LAS s16x4*)pp;
;                 if (kq == 0) o0 = __builtin_amdgcn_mfma_f32_16x16x16bf16_1k(a, vf0, o0, 0, 0, 0);
;                 else if (kq == 1) o1 = __builtin_amdgcn_mfma_f32_16x16x16bf16_1k(a, vf0, o1, 0, 0, 0);
;                 else o1 = __builtin_amdgcn_mfma_f32_16x16x16bf16_1k(a, vf1, o1, 0, 0, 0);
;             }
.LBB0_538:
	ds_read2st64_b64 v[78:81], v49 offset0:96 offset1:104
	ds_read2st64_b64 v[112:115], v49 offset0:112 offset1:120
	ds_read_u16 v33, v98 offset:46080
	ds_read_u16 v39, v98 offset:46160
	ds_read_u16 v32, v98 offset:46240
	ds_read_u16 v34, v98 offset:46320
	ds_read_u16 v36, v98 offset:47360
	ds_read_u16 v35, v98 offset:47440
	ds_read_u16 v37, v98 offset:47520
	ds_read_u16 v38, v98 offset:47600
	s_waitcnt lgkmcnt(10)
	ds_read_b64 v[130:131], v99 offset:24576
	ds_read_b64 v[132:133], v99 offset:28928
	ds_read_b64 v[134:135], v99 offset:24608
	ds_read_b64 v[136:137], v99 offset:28960
	s_waitcnt lgkmcnt(4)
	ds_read_b64 v[138:139], v100 offset:43520
	ds_read2_b64 v[140:143], v63 offset0:64 offset1:68
	ds_read_b128 v[144:147], v101 offset:48640
	ds_read_b128 v[148:151], v103 offset:48640
	ds_read2_b64 v[152:155], v109 offset0:64 offset1:68
	s_nop 0
	v_mov_b32_e32 v82, v78
	s_nop 0
	v_mov_b32_e32 v83, v112
	v_mov_b32_e32 v116, v80
	v_mov_b32_e32 v117, v114
	v_pk_add_f32 v[82:83], v[82:83], v[116:117]
	v_mov_b32_e32 v112, v79
	v_mov_b32_e32 v114, v81
	v_add_f32_e32 v73, v82, v83
	v_pk_add_f32 v[78:79], v[112:113], v[114:115]
	s_nop 0
	v_add_f32_e32 v78, v78, v79
	v_cvt_pk_bf16_f32 v79, v73, v78
	v_mul_f32_e32 v73, v73, v73
	v_fmac_f32_e32 v73, v78, v78
	global_store_dword v[76:77], v79, off
	s_nop 0
	v_add_f32_dpp v73, v73, v73 row_ror:8 row_mask:0xf bank_mask:0xf bound_ctrl:1
	s_nop 1
	v_add_f32_dpp v73, v73, v73 row_ror:4 row_mask:0xf bank_mask:0xf bound_ctrl:1
	s_nop 1
	v_add_f32_dpp v73, v73, v73 row_ror:2 row_mask:0xf bank_mask:0xf bound_ctrl:1
	s_nop 1
	v_mov_b32_dpp v78, v73 row_ror:1 row_mask:0xf bank_mask:0xf bound_ctrl:1
	s_and_saveexec_b64 s[56:57], s[14:15]
	s_cbranch_execz .LBB0_540
	v_add_f32_e32 v73, v73, v78
	global_atomic_add_f32 v[74:75], v73, off
.LBB0_540:
	s_or_b64 exec, exec, s[56:57]
	v_cvt_pk_bf16_f32 v112, v28, v29
	v_cvt_pk_bf16_f32 v113, v30, v31
	s_nop 0
	s_nop 0
	v_cvt_pk_bf16_f32 v116, v24, v25
	v_cvt_pk_bf16_f32 v117, v26, v27
	s_nop 0
	s_nop 0
	s_waitcnt lgkmcnt(8)
	v_mfma_f32_16x16x16_bf16 v[80:83], v[130:131], v[112:113], 0
	v_lshlrev_b32_e32 v39, 16, v39
	v_or_b32_sdwa v78, v39, v33 dst_sel:DWORD dst_unused:UNUSED_PAD src0_sel:DWORD src1_sel:WORD_0
	v_lshlrev_b32_e32 v33, 16, v34
	s_waitcnt lgkmcnt(7)
	v_mfma_f32_16x16x16_bf16 v[112:115], v[132:133], v[112:113], 0
	v_lshlrev_b32_e32 v39, 16, v35
	v_or_b32_sdwa v79, v33, v32 dst_sel:DWORD dst_unused:UNUSED_PAD src0_sel:DWORD src1_sel:WORD_0
	s_waitcnt lgkmcnt(6)
	v_mfma_f32_16x16x16_bf16 v[32:35], v[134:135], v[116:117], v[80:83]
	s_nop 2
	v_or_b32_sdwa v80, v39, v36 dst_sel:DWORD dst_unused:UNUSED_PAD src0_sel:DWORD src1_sel:WORD_0
	v_lshlrev_b32_e32 v36, 16, v38
	v_or_b32_sdwa v81, v36, v37 dst_sel:DWORD dst_unused:UNUSED_PAD src0_sel:DWORD src1_sel:WORD_0
	s_waitcnt lgkmcnt(5)
	v_mfma_f32_16x16x16_bf16 v[36:39], v[136:137], v[116:117], v[112:115]
	s_and_saveexec_b64 s[56:57], s[16:17]
	s_cbranch_execz .LBB0_550
	s_nop 0
	s_and_saveexec_b64 s[36:37], s[42:43]
	s_xor_b64 s[58:59], exec, s[36:37]
	s_cbranch_execz .LBB0_547
	s_and_saveexec_b64 s[36:37], s[18:19]
	s_xor_b64 s[60:61], exec, s[36:37]
	s_cbranch_execz .LBB0_544
	s_waitcnt lgkmcnt(4)
	v_mfma_f32_16x16x16_bf16 v[36:39], v[138:139], v[80:81], v[36:39]
.LBB0_544:
	s_andn2_saveexec_b64 s[60:61], s[60:61]
	s_cbranch_execz .LBB0_546
	s_waitcnt lgkmcnt(4)
	v_mfma_f32_16x16x16_bf16 v[36:39], v[138:139], v[78:79], v[36:39]

; #define LAS __attribute__((address_space(3)))
; __device__ __forceinline__ void hg_recur(LAS unsigned char* lds, const bf16_t* QF, bf16_t* IG, const bf16_t* P, const float* Dg, float* ssq_o, int G, int bid) {
;     ...
;             if (kq < 3) {
;                 const LAS unsigned char* pp = sb + H3_P + (16 * (kq > 0 ? 1 : 0) + lv) * H3_PP + (16 * (kq == 2 ? 1 : 0) + 4 * fq) * 2;
;                 const s16x4 a = *(const LAS s16x4*)pp;
;                 if (kq == 0) o0 = __builtin_amdgcn_mfma_f32_16x16x16bf16_1k(a, vf0, o0, 0, 0, 0);
;                 else if (kq == 1) o1 = __builtin_amdgcn_mfma_f32_16x16x16bf16_1k(a, vf0, o1, 0, 0, 0);
;                 else o1 = __builtin_amdgcn_mfma_f32_16x16x16bf16_1k(a, vf1, o1, 0, 0, 0);
.LBB0_547:
	s_andn2_saveexec_b64 s[58:59], s[58:59]
	s_cbranch_execz .LBB0_549
	s_waitcnt lgkmcnt(4)
	v_mfma_f32_16x16x16_bf16 v[32:35], v[138:139], v[78:79], v[32:35]

; #define LAS __attribute__((address_space(3)))
; #define LDS_BARRIER() do { asm volatile("s_waitcnt lgkmcnt(0)" ::: "memory"); __builtin_amdgcn_s_barrier(); asm volatile("" ::: "memory"); } while (0)
; __device__ __forceinline__ void hg_recur(LAS unsigned char* lds, const bf16_t* QF, bf16_t* IG, const bf16_t* P, const float* Dg, float* ssq_o, int G, int bid) {
;     ...
; #pragma unroll
;             for (int k2 = 0; k2 < 2; ++k2) {
;                 const f32x4 dd = *(const LAS f32x4*)(sb + H3_D + (32 * kq + 16 * k2 + 4 * fq) * 4);
;                 S[k2] = S[k2] * dd;
;                 const LAS unsigned char* kp = sb + H3_K + (32 * kq + 16 * k2 + lv) * H3_KP + 4 * fq * 2;
;                 const s16x4 a0 = *(const LAS s16x4*)kp, a1 = *(const LAS s16x4*)(kp + 32);
;                 S[k2] = __builtin_amdgcn_mfma_f32_16x16x16bf16_1k(a0, vf0, S[k2], 0, 0, 0);
;                 S[k2] = __builtin_amdgcn_mfma_f32_16x16x16bf16_1k(a1, vf1, S[k2], 0, 0, 0);
;             }
;             { LAS float* ot = (LAS float*)(lds + H3_O + st * H3_OBYTES) + kq * 1024 + 16 * vt + lv;
; #pragma unroll
;               for (int i = 0; i < 4; ++i) { ot[(4 * fq + i) * 32] = o0[i]; ot[(16 + 4 * fq + i) * 32] = o1[i]; } }
;             LDS_BARRIER();
.LBB0_550:
	s_or_b64 exec, exec, s[56:57]
	s_nop 0
	s_nop 0
	s_nop 0
	v_add_u32_e32 v72, 64, v72
	v_lshl_add_u64 v[74:75], v[74:75], 0, s[46:47]
	v_lshl_add_u64 v[76:77], v[76:77], 0, s[48:49]
	s_waitcnt lgkmcnt(2)
	v_pk_mul_f32 v[30:31], v[30:31], v[146:147]
	v_pk_mul_f32 v[28:29], v[28:29], v[144:145]
	s_nop 0
	s_waitcnt lgkmcnt(1)
	v_pk_mul_f32 v[26:27], v[26:27], v[150:151]
	v_pk_mul_f32 v[24:25], v[24:25], v[148:149]
	v_mfma_f32_16x16x16_bf16 v[28:31], v[140:141], v[78:79], v[28:31]
	ds_write2_b32 v110, v32, v33 offset1:32
	ds_write2_b32 v111, v36, v37 offset1:32
	ds_write2_b32 v110, v34, v35 offset0:64 offset1:96
	ds_write2_b32 v111, v38, v39 offset0:64 offset1:96
	s_waitcnt lgkmcnt(0)
	s_waitcnt lgkmcnt(4)
	v_mfma_f32_16x16x16_bf16 v[24:27], v[152:153], v[78:79], v[24:27]
	s_barrier
	s_and_b64 vcc, exec, s[54:55]
	v_mfma_f32_16x16x16_bf16 v[28:31], v[142:143], v[80:81], v[28:31]
	v_mfma_f32_16x16x16_bf16 v[24:27], v[154:155], v[80:81], v[24:27]
	s_cbranch_vccnz .LBB0_552
	s_mov_b32 s35, s33
	s_branch .LBB0_484
